# thr
# speedup vs baseline: 1.0052x; 1.0052x over previous
; __device__ __forceinline__ int opaque_tid() { int t = threadIdx.x; asm volatile("" : "+v"(t)); return t; }
; __device__ void phase_attn(const Params& p, char* smem) {
;   const int tid = opaque_tid(), lane = tid & 63, w = tid >> 6;
;   const int l15 = lane & 15, lq = lane >> 4;
;   char* ws = p.ws;
;   const bf16_t* qk = (const bf16_t*)(ws + OFF_B);
;   const bf16_t* vT = (const bf16_t*)(ws + OFF_B_VT);
;   const bf16_t* bcx = (const bf16_t*)(ws + OFF_B_BCX);
;   bf16_t* mixed = (bf16_t*)(ws + OFF_A);
;   bf16_t* sP = (bf16_t*)smem + w * (32 * 72);
;   float* sSsq = (float*)(smem + 4 * 32 * 72 * 2);
;   float* sO = (float*)(smem + 20480) + w * 2048;
;   const float mk1 = (l15 & 1) ? 0.f : 1.f, mk2 = (l15 & 2) ? 0.f : 1.f, mk4 = (l15 & 4) ? 0.f : 1.f, mk8 = (l15 & 8) ? 0.f : 1.f;
;   const int cgrp = (gridDim.x >= 2) ? (int)(blockIdx.x & 1) : 0;
;   const int cg_idx = (gridDim.x >= 2) ? (int)(blockIdx.x >> 1) : 0;
;   const int cg_size = (gridDim.x >= 2) ? (int)((gridDim.x + 1 - cgrp) >> 1) : 1;
;     ...
;         if (__all(mx < -158.7f)) break;
.LBB0_221:
	v_ashrrev_i32_e32 v9, 6, v22
	s_movk_i32 s4, 0x1200
	v_mul_lo_u32 v0, v9, s4
	s_movk_i32 s4, 0xe00
	v_mad_u64_u32 v[2:3], s[4:5], v9, s4, v[0:1]
	v_and_b32_e32 v1, 1, v22
	v_cmp_eq_u32_e32 vcc, 0, v1
	v_and_b32_e32 v1, 2, v22
	v_lshlrev_b32_e32 v128, 7, v9
	v_cndmask_b32_e64 v153, 0, 1.0, vcc
	v_cmp_eq_u32_e32 vcc, 0, v1
	v_and_b32_e32 v1, 4, v22
	v_mov_b32_e32 v132, 0
	v_and_b32_e32 v8, 63, v22
	v_and_b32_e32 v151, 15, v22
	v_cndmask_b32_e64 v155, 0, 1.0, vcc
	v_cmp_eq_u32_e32 vcc, 0, v1
	v_and_b32_e32 v1, 8, v22
	v_and_b32_e32 v130, 48, v22
	v_mov_b32_e32 v131, v132
	v_ashrrev_i32_e32 v129, 31, v128
	v_cndmask_b32_e64 v180, 0, 1.0, vcc
	v_cmp_eq_u32_e32 vcc, 0, v1
	v_lshl_add_u64 v[4:5], s[20:21], 0, v[130:131]
	v_lshlrev_b32_e32 v6, 1, v151
	v_mul_u32_u24_e32 v1, 0x90, v151
	v_lshl_or_b32 v184, v8, 2, v2
	v_mov_b32_e32 v7, v132
	v_lshlrev_b64 v[2:3], 1, v[128:129]
	v_bfe_u32 v10, v22, 4, 2
	v_or_b32_e32 v11, v0, v6
	v_add3_u32 v183, v0, v1, v130
	v_lshl_add_u64 v[0:1], s[12:13], 0, v[6:7]
	v_lshl_add_u64 v[136:137], v[4:5], 0, v[2:3]
	v_lshlrev_b32_e32 v4, 5, v8
	v_mov_b32_e32 v5, v132
	v_lshlrev_b32_e32 v182, 2, v10
	v_mul_u32_u24_e32 v6, 0x240, v10
	v_lshl_add_u64 v[138:139], s[24:25], 0, v[4:5]
	s_mov_b64 s[6:7], 0x1000
	v_lshl_add_u64 v[4:5], s[20:21], 0, v[2:3]
	v_lshl_add_u64 v[144:145], v[0:1], 0, v[2:3]
	v_mbcnt_lo_u32_b32 v0, -1, 0
	s_mov_b32 s37, 0
	v_cndmask_b32_e64 v181, 0, 1.0, vcc
	v_lshl_add_u64 v[134:135], s[14:15], 0, v[130:131]
	v_cmp_eq_u32_e64 s[4:5], 0, v151
	v_lshlrev_b32_e32 v185, 3, v9
	v_or_b32_e32 v186, 64, v128
	v_or_b32_e32 v187, 1, v182
	v_or_b32_e32 v188, 2, v182
	v_or_b32_e32 v189, 3, v182
	v_or_b32_e32 v190, 16, v182
	v_or_b32_e32 v191, 17, v182
	v_or_b32_e32 v194, 18, v182
	v_or_b32_e32 v195, 19, v182
	v_lshl_add_u64 v[140:141], v[138:139], 0, s[6:7]
	v_lshl_add_u64 v[142:143], v[4:5], 0, v[130:131]
	s_lshl_b32 s25, s2, 5
	s_lshl_b32 s39, s34, 5
	v_lshlrev_b32_e32 v146, 4, v8
	v_mov_b32_e32 v147, v132
	s_mov_b32 s24, 0x3e38aa3b
	s_mov_b32 s41, 0xbe38aa3b
	v_add_u32_e32 v196, v11, v6
	s_mov_b32 s46, 0xc3060000
	s_mov_b32 s38, 0x3b000000
	s_mov_b32 s40, 0x358637bd
	s_mov_b32 s47, 0x800000
	s_movk_i32 s52, 0x7fff
	s_movk_i32 s53, 0xc00
	s_mov_b32 s65, 0xb7a0000
	v_mov_b32_e32 v198, 0x358637bd
	s_mov_b64 s[42:43], 0xc00
	s_mov_b64 s[44:45], 0x800
	v_mbcnt_hi_u32_b32 v199, -1, v0
	v_mov_b32_e32 v200, 1
	s_mov_b32 s66, s2
	s_branch .LBB0_223
